# combination of the small attention edits (prologue rotation, batched tile-0 K fragment reads, LDS-store wait placement, dense ballot trim)
# speedup vs baseline: 1.0005x; 1.0005x over previous
.Lwin_fx:
	s_movk_i32 s5, 0x90
	v_mul_lo_u32 v23, v194, s5
	s_or_b32 s5, s28, 63
	s_add_i32 s16, s20, 0xffffff80
	s_cmp_ge_i32 s5, s16
	s_cselect_b64 s[8:9], -1, 0
	s_add_i32 s17, s20, 0x9f
	s_cmp_le_i32 s28, s17
	s_cselect_b64 s[14:15], -1, 0
	s_and_b64 s[8:9], s[8:9], s[14:15]
	v_and_b32_e32 v17, 31, v17
	s_or_b64 s[2:3], s[2:3], s[8:9]
	v_add3_u32 v195, 0, v23, v22
	s_andn2_b64 vcc, exec, s[2:3]
	s_waitcnt vmcnt(7)
	v_mul_u32_u24_e32 v196, 0x90, v17
	s_waitcnt vmcnt(2)
	ds_write_b128 v195, v[18:21]
	s_waitcnt lgkmcnt(0)
	s_barrier
	s_cbranch_vccnz .LBB0_487
	v_add3_u32 v22, 0, v196, v0
	ds_read_b128 v[144:147], v22
	ds_read_b128 v[148:151], v22 offset:4608
	ds_read_b128 v[152:155], v22 offset:32
	ds_read_b128 v[156:159], v22 offset:4640
	ds_read_b128 v[160:163], v22 offset:64
	ds_read_b128 v[164:167], v22 offset:4672
	ds_read_b128 v[168:171], v22 offset:96
	ds_read_b128 v[172:175], v22 offset:4704
	s_andn2_b64 vcc, exec, s[0:1]
	s_waitcnt lgkmcnt(7)
	v_mfma_f32_32x32x16_bf16 v[48:63], v[144:147], v[2:5], 0
	s_waitcnt lgkmcnt(6)
	v_mfma_f32_32x32x16_bf16 v[64:79], v[148:151], v[2:5], 0
	s_waitcnt lgkmcnt(5)
	v_mfma_f32_32x32x16_bf16 v[48:63], v[152:155], v[6:9], v[48:63]
	s_waitcnt lgkmcnt(4)
	v_mfma_f32_32x32x16_bf16 v[64:79], v[156:159], v[6:9], v[64:79]
	s_waitcnt lgkmcnt(3)
	v_mfma_f32_32x32x16_bf16 v[48:63], v[160:163], v[10:13], v[48:63]
	s_waitcnt lgkmcnt(2)
	v_mfma_f32_32x32x16_bf16 v[64:79], v[164:167], v[10:13], v[64:79]
	s_waitcnt lgkmcnt(1)
	v_mfma_f32_32x32x16_bf16 v[48:63], v[168:171], v[176:179], v[48:63]
	s_waitcnt lgkmcnt(0)
	v_mfma_f32_32x32x16_bf16 v[64:79], v[172:175], v[176:179], v[64:79]
	s_cbranch_vccnz .LBB0_486
	s_add_i32 s0, s20, 0xffffff9f
	s_cmp_lt_i32 s28, s0
	s_cselect_b64 s[0:1], -1, 0
	s_add_i32 s5, s20, 0x41
	s_cmp_gt_i32 s28, s5
	s_cselect_b64 s[8:9], -1, 0
	s_or_b64 s[0:1], s[0:1], s[8:9]
	s_andn2_b64 vcc, exec, s[0:1]
	s_cbranch_vccnz .LBB0_486
	v_or_b32_e32 v18, s20, v17
	v_lshl_or_b32 v19, v226, 2, s28
	v_sub_u32_e32 v18, v18, v19
	v_add_u32_e32 v19, 0x80, v18
	s_movk_i32 s0, 0x101
	v_cmp_gt_u32_e32 vcc, s0, v19
	v_add_u32_e32 v19, 0xffffff5f, v18
	s_movk_i32 s0, 0xfefe
	v_cndmask_b32_e32 v48, v216, v48, vcc
	v_cmp_lt_u32_e32 vcc, s0, v19
	v_add_u32_e32 v19, 0xffffff7e, v18
	s_nop 0
	v_cndmask_b32_e32 v64, v216, v64, vcc
	v_cmp_lt_u32_e32 vcc, s0, v19
	v_add_u32_e32 v19, 0xffffff5e, v18
	s_nop 0
	v_cndmask_b32_e32 v49, v216, v49, vcc
	v_cmp_lt_u32_e32 vcc, s0, v19
	v_add_u32_e32 v19, 0xffffff7d, v18
	s_nop 0
	v_cndmask_b32_e32 v65, v216, v65, vcc
	v_cmp_lt_u32_e32 vcc, s0, v19
	v_add_u32_e32 v19, 0xffffff5d, v18
	s_nop 0
	v_cndmask_b32_e32 v50, v216, v50, vcc
	v_cmp_lt_u32_e32 vcc, s0, v19
	v_add_u32_e32 v19, 0xffffff7c, v18
	s_nop 0
	v_cndmask_b32_e32 v66, v216, v66, vcc
	v_cmp_lt_u32_e32 vcc, s0, v19
	v_add_u32_e32 v19, 0xffffff5c, v18
	s_nop 0
	v_cndmask_b32_e32 v51, v216, v51, vcc
	v_cmp_lt_u32_e32 vcc, s0, v19
	v_add_u32_e32 v19, 0xffffff77, v18
	s_nop 0
	v_cndmask_b32_e32 v67, v216, v67, vcc
	v_cmp_lt_u32_e32 vcc, s0, v19
	v_add_u32_e32 v19, 0xffffff57, v18
	s_nop 0
	v_cndmask_b32_e32 v52, v216, v52, vcc
	v_cmp_lt_u32_e32 vcc, s0, v19
	v_add_u32_e32 v19, 0xffffff76, v18
	s_nop 0
	v_cndmask_b32_e32 v68, v216, v68, vcc
	v_cmp_lt_u32_e32 vcc, s0, v19
	v_add_u32_e32 v19, 0xffffff56, v18
	s_nop 0
	v_cndmask_b32_e32 v53, v216, v53, vcc
	v_cmp_lt_u32_e32 vcc, s0, v19
	v_add_u32_e32 v19, 0xffffff75, v18
	s_nop 0
	v_cndmask_b32_e32 v69, v216, v69, vcc
	v_cmp_lt_u32_e32 vcc, s0, v19
	v_add_u32_e32 v19, 0xffffff55, v18
	s_nop 0
	v_cndmask_b32_e32 v54, v216, v54, vcc
	v_cmp_lt_u32_e32 vcc, s0, v19
	v_add_u32_e32 v19, 0xffffff74, v18
	s_nop 0
	v_cndmask_b32_e32 v70, v216, v70, vcc
	v_cmp_lt_u32_e32 vcc, s0, v19
	v_add_u32_e32 v19, 0xffffff54, v18
	s_nop 0
	v_cndmask_b32_e32 v55, v216, v55, vcc
	v_cmp_lt_u32_e32 vcc, s0, v19
	v_add_u32_e32 v19, 0xffffff6f, v18
	s_nop 0
	v_cndmask_b32_e32 v71, v216, v71, vcc
	v_cmp_lt_u32_e32 vcc, s0, v19
	v_add_u32_e32 v19, 0xffffff4f, v18
	s_nop 0
	v_cndmask_b32_e32 v56, v216, v56, vcc
	v_cmp_lt_u32_e32 vcc, s0, v19
	v_add_u32_e32 v19, 0xffffff6e, v18
	s_nop 0
	v_cndmask_b32_e32 v72, v216, v72, vcc
	v_cmp_lt_u32_e32 vcc, s0, v19
	v_add_u32_e32 v19, 0xffffff4e, v18
	s_nop 0
	v_cndmask_b32_e32 v57, v216, v57, vcc
	v_cmp_lt_u32_e32 vcc, s0, v19
	v_add_u32_e32 v19, 0xffffff6d, v18
	s_nop 0
	v_cndmask_b32_e32 v73, v216, v73, vcc
	v_cmp_lt_u32_e32 vcc, s0, v19
	v_add_u32_e32 v19, 0xffffff4d, v18
	s_nop 0
	v_cndmask_b32_e32 v58, v216, v58, vcc
	v_cmp_lt_u32_e32 vcc, s0, v19
	v_add_u32_e32 v19, 0xffffff6c, v18
	s_nop 0
	v_cndmask_b32_e32 v74, v216, v74, vcc
	v_cmp_lt_u32_e32 vcc, s0, v19
	v_add_u32_e32 v19, 0xffffff4c, v18
	s_nop 0
	v_cndmask_b32_e32 v59, v216, v59, vcc
	v_cmp_lt_u32_e32 vcc, s0, v19
	v_add_u32_e32 v19, 0xffffff67, v18
	s_nop 0
	v_cndmask_b32_e32 v75, v216, v75, vcc
	v_cmp_lt_u32_e32 vcc, s0, v19
	v_add_u32_e32 v19, 0xffffff47, v18
	s_nop 0
	v_cndmask_b32_e32 v60, v216, v60, vcc
	v_cmp_lt_u32_e32 vcc, s0, v19
	v_add_u32_e32 v19, 0xffffff66, v18
	s_nop 0
	v_cndmask_b32_e32 v76, v216, v76, vcc
	v_cmp_lt_u32_e32 vcc, s0, v19
	v_add_u32_e32 v19, 0xffffff46, v18
	s_nop 0
	v_cndmask_b32_e32 v61, v216, v61, vcc
	v_cmp_lt_u32_e32 vcc, s0, v19
	v_add_u32_e32 v19, 0xffffff65, v18
	s_nop 0
	v_cndmask_b32_e32 v77, v216, v77, vcc
	v_cmp_lt_u32_e32 vcc, s0, v19
	v_add_u32_e32 v19, 0xffffff45, v18
	s_nop 0
	v_cndmask_b32_e32 v62, v216, v62, vcc
	v_cmp_lt_u32_e32 vcc, s0, v19
	v_add_u32_e32 v19, 0xffffff64, v18
	v_add_u32_e32 v18, 0xffffff44, v18
	v_cndmask_b32_e32 v78, v216, v78, vcc
	v_cmp_lt_u32_e32 vcc, s0, v19
	s_nop 1
	v_cndmask_b32_e32 v63, v216, v63, vcc
	v_cmp_lt_u32_e32 vcc, s0, v18
	s_nop 1
	v_cndmask_b32_e32 v79, v216, v79, vcc

.LBB0_539:
	s_andn2_b64 s[4:5], exec, s[2:3]
	s_andn2_b64 vcc, exec, s[2:3]
	s_cbranch_vccnz .LBB0_541
	s_add_i32 s2, s28, 35
	s_cmp_lt_u32 s27, s23
	s_cselect_b32 s2, s27, s2
	s_lshl_b32 s68, s2, 6
	v_lshl_add_u64 v[34:35], s[68:69], 1, v[114:115]
	global_load_dwordx4 v[94:97], v[34:35], off
